# scan compute loop: adjacent lgkmcnt wait pairs merged into one wait (14 fewer s_waitcnt per chunk)
# baseline (speedup 1.0000x reference)
.LBB0_1050:
	ds_read_b128 v[14:17], v0 offset:20480
	ds_read_b128 v[10:13], v0 offset:20496
	ds_read_b128 v[6:9], v0 offset:20512
	ds_read_b128 v[2:5], v0 offset:20528
	ds_read_b128 v[54:57], v89 offset:16384
	ds_read_b128 v[26:29], v89 offset:16640
	ds_read_b128 v[78:81], v89 offset:4096
	ds_read_b128 v[58:61], v89 offset:4352
	ds_read_b128 v[30:33], v89 offset:4608
	ds_read_b128 v[22:25], v90 offset:8704
	ds_read_b128 v[18:21], v89 offset:16896
	v_pk_mul_f32 v[66:67], v[74:75], v[108:109]
	s_waitcnt lgkmcnt(4)
	v_pk_mul_f32 v[78:79], v[14:15], v[78:79] op_sel_hi:[0,1]
	v_pk_fma_f32 v[66:67], v[76:77], v[110:111], v[66:67]
	v_pk_mul_f32 v[80:81], v[14:15], v[80:81] op_sel_hi:[0,1]
	v_add_f32_e32 v66, v66, v67
	v_pk_fma_f32 v[62:63], v[74:75], v[100:101], v[78:79]
	v_pk_fma_f32 v[64:65], v[76:77], v[102:103], v[80:81]
	v_add_f32_dpp v66, v66, v66 quad_perm:[1,0,3,2] row_mask:0xf bank_mask:0xf bound_ctrl:1
	v_mov_b32_e32 v0, v17
	v_mov_b32_e32 v82, v13
	v_add_f32_dpp v66, v66, v66 quad_perm:[2,3,0,1] row_mask:0xf bank_mask:0xf bound_ctrl:1
	v_mov_b32_e32 v84, v9
	v_mov_b32_e32 v86, v5
	v_add_f32_dpp v66, v66, v66 row_half_mirror row_mask:0xf bank_mask:0xf bound_ctrl:1
	s_add_i32 s26, s26, 1
	s_nop 0
	v_add_f32_dpp v66, v66, v66 row_ror:8 row_mask:0xf bank_mask:0xf bound_ctrl:1
	v_pk_fma_f32 v[62:63], v[120:121], v[66:67], v[62:63] op_sel_hi:[1,0,1] neg_lo:[1,0,0] neg_hi:[1,0,0]
	v_pk_fma_f32 v[64:65], v[122:123], v[66:67], v[64:65] op_sel_hi:[1,0,1] neg_lo:[1,0,0] neg_hi:[1,0,0]
	v_pk_mul_f32 v[50:51], v[112:113], v[62:63]
	v_pk_mul_f32 v[46:47], v[104:105], v[62:63]
	v_pk_fma_f32 v[50:51], v[114:115], v[64:65], v[50:51]
	s_waitcnt lgkmcnt(3)
	v_pk_fma_f32 v[66:67], v[14:15], v[58:59], v[46:47] op_sel:[1,0,0]
	v_add_f32_e32 v47, v50, v51
	v_pk_mul_f32 v[48:49], v[106:107], v[64:65]
	v_pk_mul_f32 v[56:57], v[56:57], v[64:65]
	v_add_f32_dpp v68, v47, v47 quad_perm:[1,0,3,2] row_mask:0xf bank_mask:0xf bound_ctrl:1
	v_pk_fma_f32 v[14:15], v[14:15], v[60:61], v[48:49] op_sel:[1,0,0]
	v_pk_fma_f32 v[54:55], v[54:55], v[62:63], v[56:57]
	v_add_f32_dpp v68, v68, v68 quad_perm:[2,3,0,1] row_mask:0xf bank_mask:0xf bound_ctrl:1
	v_add_f32_e32 v92, v54, v55
	s_nop 0
	v_add_f32_dpp v68, v68, v68 row_half_mirror row_mask:0xf bank_mask:0xf bound_ctrl:1
	ds_read_b128 v[46:49], v90 offset:768
	ds_read_b128 v[50:53], v89 offset:4864
	ds_read_b128 v[54:57], v90 offset:4864
	ds_read_b128 v[58:61], v90 offset:8960
	ds_read_b128 v[62:65], v89 offset:17152
	v_add_f32_dpp v68, v68, v68 row_ror:8 row_mask:0xf bank_mask:0xf bound_ctrl:1
	v_pk_fma_f32 v[42:43], v[128:129], v[68:69], v[66:67] op_sel_hi:[1,0,1] neg_lo:[1,0,0] neg_hi:[1,0,0]
	v_pk_fma_f32 v[14:15], v[130:131], v[68:69], v[14:15] op_sel_hi:[1,0,1] neg_lo:[1,0,0] neg_hi:[1,0,0]
	v_pk_mul_f32 v[38:39], v[124:125], v[42:43]
	v_pk_mul_f32 v[28:29], v[28:29], v[14:15]
	v_pk_mul_f32 v[36:37], v[118:119], v[14:15]
	v_pk_fma_f32 v[14:15], v[126:127], v[14:15], v[38:39]
	v_pk_mul_f32 v[34:35], v[116:117], v[42:43]
	v_add_f32_e32 v14, v14, v15
	v_pk_fma_f32 v[26:27], v[26:27], v[42:43], v[28:29]
	s_waitcnt lgkmcnt(7)
	v_pk_fma_f32 v[42:43], v[16:17], v[30:31], v[34:35] op_sel_hi:[0,1,1]
	v_add_f32_dpp v66, v14, v14 quad_perm:[1,0,3,2] row_mask:0xf bank_mask:0xf bound_ctrl:1
	v_pk_fma_f32 v[44:45], v[16:17], v[32:33], v[36:37] op_sel_hi:[0,1,1]
	v_add_f32_e32 v93, v26, v27
	v_add_f32_dpp v66, v66, v66 quad_perm:[2,3,0,1] row_mask:0xf bank_mask:0xf bound_ctrl:1
	ds_read_b128 v[14:17], v90 offset:1024
	ds_read_b128 v[26:29], v89 offset:5120
	ds_read_b128 v[30:33], v90 offset:5120
	ds_read_b128 v[34:37], v90 offset:9216
	ds_read_b128 v[38:41], v89 offset:17408
	v_add_f32_dpp v66, v66, v66 row_half_mirror row_mask:0xf bank_mask:0xf bound_ctrl:1
	s_nop 1
	v_add_f32_dpp v66, v66, v66 row_ror:8 row_mask:0xf bank_mask:0xf bound_ctrl:1
	s_waitcnt lgkmcnt(7)
	v_pk_fma_f32 v[22:23], v[22:23], v[66:67], v[42:43] op_sel_hi:[1,0,1] neg_lo:[1,0,0] neg_hi:[1,0,0]
	v_pk_fma_f32 v[24:25], v[24:25], v[66:67], v[44:45] op_sel_hi:[1,0,1] neg_lo:[1,0,0] neg_hi:[1,0,0]
	v_pk_mul_f32 v[42:43], v[54:55], v[22:23]
	v_pk_mul_f32 v[20:21], v[20:21], v[24:25]
	v_pk_mul_f32 v[44:45], v[46:47], v[22:23]
	v_pk_mul_f32 v[46:47], v[48:49], v[24:25]
	v_pk_fma_f32 v[18:19], v[18:19], v[22:23], v[20:21]
	v_pk_fma_f32 v[20:21], v[56:57], v[24:25], v[42:43]
	v_pk_fma_f32 v[54:55], v[0:1], v[50:51], v[44:45] op_sel_hi:[0,1,1]
	v_pk_fma_f32 v[56:57], v[0:1], v[52:53], v[46:47] op_sel_hi:[0,1,1]
	v_add_f32_e32 v94, v18, v19
	v_add_f32_e32 v18, v20, v21
	s_nop 0
	s_nop 0
	v_add_f32_dpp v0, v18, v18 quad_perm:[1,0,3,2] row_mask:0xf bank_mask:0xf bound_ctrl:1
	ds_read_b128 v[18:21], v90 offset:1280
	ds_read_b128 v[22:25], v89 offset:5376
	v_add_f32_dpp v0, v0, v0 quad_perm:[2,3,0,1] row_mask:0xf bank_mask:0xf bound_ctrl:1
	ds_read_b128 v[42:45], v90 offset:5376
	ds_read_b128 v[46:49], v90 offset:9472
	v_add_f32_dpp v0, v0, v0 row_half_mirror row_mask:0xf bank_mask:0xf bound_ctrl:1
	ds_read_b128 v[50:53], v89 offset:17664
	s_nop 0
	v_add_f32_dpp v0, v0, v0 row_ror:8 row_mask:0xf bank_mask:0xf bound_ctrl:1
	s_waitcnt lgkmcnt(7)
	v_pk_fma_f32 v[54:55], v[58:59], v[0:1], v[54:55] op_sel_hi:[1,0,1] neg_lo:[1,0,0] neg_hi:[1,0,0]
	v_pk_fma_f32 v[56:57], v[60:61], v[0:1], v[56:57] op_sel_hi:[1,0,1] neg_lo:[1,0,0] neg_hi:[1,0,0]
	v_pk_mul_f32 v[30:31], v[30:31], v[54:55]
	v_pk_mul_f32 v[58:59], v[64:65], v[56:57]
	v_pk_mul_f32 v[14:15], v[14:15], v[54:55]
	v_pk_fma_f32 v[54:55], v[62:63], v[54:55], v[58:59]
	v_pk_fma_f32 v[30:31], v[32:33], v[56:57], v[30:31]
	v_pk_fma_f32 v[62:63], v[10:11], v[26:27], v[14:15] op_sel_hi:[0,1,1]
	v_add_f32_e32 v95, v54, v55
	v_add_f32_e32 v14, v30, v31
	ds_write_b128 v91, v[92:95] offset:43008
	v_pk_mul_f32 v[16:17], v[16:17], v[56:57]
	v_add_f32_dpp v0, v14, v14 quad_perm:[1,0,3,2] row_mask:0xf bank_mask:0xf bound_ctrl:1
	v_pk_fma_f32 v[64:65], v[10:11], v[28:29], v[16:17] op_sel_hi:[0,1,1]
	ds_read_b128 v[14:17], v90 offset:1536
	v_add_f32_dpp v0, v0, v0 quad_perm:[2,3,0,1] row_mask:0xf bank_mask:0xf bound_ctrl:1
	ds_read_b128 v[26:29], v89 offset:5632
	ds_read_b128 v[30:33], v90 offset:5632
	v_add_f32_dpp v0, v0, v0 row_half_mirror row_mask:0xf bank_mask:0xf bound_ctrl:1
	ds_read_b128 v[54:57], v90 offset:9728
	ds_read_b128 v[58:61], v89 offset:17920
	v_add_f32_dpp v0, v0, v0 row_ror:8 row_mask:0xf bank_mask:0xf bound_ctrl:1
	s_waitcnt lgkmcnt(8)
	v_pk_fma_f32 v[34:35], v[34:35], v[0:1], v[62:63] op_sel_hi:[1,0,1] neg_lo:[1,0,0] neg_hi:[1,0,0]
	v_pk_fma_f32 v[36:37], v[36:37], v[0:1], v[64:65] op_sel_hi:[1,0,1] neg_lo:[1,0,0] neg_hi:[1,0,0]
	v_pk_mul_f32 v[42:43], v[42:43], v[34:35]
	v_pk_mul_f32 v[40:41], v[40:41], v[36:37]
	v_pk_mul_f32 v[18:19], v[18:19], v[34:35]
	v_pk_mul_f32 v[20:21], v[20:21], v[36:37]
	v_pk_fma_f32 v[34:35], v[38:39], v[34:35], v[40:41]
	v_pk_fma_f32 v[36:37], v[44:45], v[36:37], v[42:43]
	v_pk_fma_f32 v[62:63], v[10:11], v[22:23], v[18:19] op_sel:[1,0,0]
	v_add_f32_e32 v18, v36, v37
	v_add_f32_e32 v96, v34, v35
	v_pk_fma_f32 v[10:11], v[10:11], v[24:25], v[20:21] op_sel:[1,0,0]
	v_add_f32_dpp v0, v18, v18 quad_perm:[1,0,3,2] row_mask:0xf bank_mask:0xf bound_ctrl:1
	ds_read_b128 v[18:21], v90 offset:1792
	ds_read_b128 v[22:25], v89 offset:5888
	v_add_f32_dpp v0, v0, v0 quad_perm:[2,3,0,1] row_mask:0xf bank_mask:0xf bound_ctrl:1
	ds_read_b128 v[34:37], v90 offset:5888
	ds_read_b128 v[38:41], v90 offset:9984
	v_add_f32_dpp v0, v0, v0 row_half_mirror row_mask:0xf bank_mask:0xf bound_ctrl:1
	ds_read_b128 v[42:45], v89 offset:18176
	s_nop 0
	v_add_f32_dpp v0, v0, v0 row_ror:8 row_mask:0xf bank_mask:0xf bound_ctrl:1
	s_waitcnt lgkmcnt(7)
	v_pk_fma_f32 v[46:47], v[46:47], v[0:1], v[62:63] op_sel_hi:[1,0,1] neg_lo:[1,0,0] neg_hi:[1,0,0]
	v_pk_fma_f32 v[10:11], v[48:49], v[0:1], v[10:11] op_sel_hi:[1,0,1] neg_lo:[1,0,0] neg_hi:[1,0,0]
	v_pk_mul_f32 v[30:31], v[30:31], v[46:47]
	v_pk_mul_f32 v[48:49], v[52:53], v[10:11]
	v_pk_mul_f32 v[14:15], v[14:15], v[46:47]
	v_pk_mul_f32 v[16:17], v[16:17], v[10:11]
	v_pk_fma_f32 v[46:47], v[50:51], v[46:47], v[48:49]
	v_pk_fma_f32 v[10:11], v[32:33], v[10:11], v[30:31]
	v_add_f32_e32 v10, v10, v11
	v_add_f32_e32 v97, v46, v47
	v_pk_fma_f32 v[50:51], v[12:13], v[26:27], v[14:15] op_sel_hi:[0,1,1]
	v_add_f32_dpp v0, v10, v10 quad_perm:[1,0,3,2] row_mask:0xf bank_mask:0xf bound_ctrl:1
	v_pk_fma_f32 v[52:53], v[12:13], v[28:29], v[16:17] op_sel_hi:[0,1,1]
	ds_read_b128 v[10:13], v90 offset:2048
	v_add_f32_dpp v0, v0, v0 quad_perm:[2,3,0,1] row_mask:0xf bank_mask:0xf bound_ctrl:1
	ds_read_b128 v[14:17], v89 offset:6144
	ds_read_b128 v[26:29], v90 offset:6144
	v_add_f32_dpp v0, v0, v0 row_half_mirror row_mask:0xf bank_mask:0xf bound_ctrl:1
	ds_read_b128 v[30:33], v90 offset:10240
	ds_read_b128 v[46:49], v89 offset:18432
	v_add_f32_dpp v0, v0, v0 row_ror:8 row_mask:0xf bank_mask:0xf bound_ctrl:1
	s_waitcnt lgkmcnt(7)
	v_pk_fma_f32 v[50:51], v[54:55], v[0:1], v[50:51] op_sel_hi:[1,0,1] neg_lo:[1,0,0] neg_hi:[1,0,0]
	v_pk_fma_f32 v[52:53], v[56:57], v[0:1], v[52:53] op_sel_hi:[1,0,1] neg_lo:[1,0,0] neg_hi:[1,0,0]
	v_pk_mul_f32 v[34:35], v[34:35], v[50:51]
	v_pk_mul_f32 v[54:55], v[60:61], v[52:53]
	v_pk_mul_f32 v[18:19], v[18:19], v[50:51]
	v_pk_fma_f32 v[50:51], v[58:59], v[50:51], v[54:55]
	v_pk_fma_f32 v[34:35], v[36:37], v[52:53], v[34:35]
	v_pk_fma_f32 v[58:59], v[82:83], v[22:23], v[18:19] op_sel_hi:[0,1,1]
	v_add_f32_e32 v18, v34, v35
	v_add_f32_e32 v98, v50, v51
	v_pk_mul_f32 v[20:21], v[20:21], v[52:53]
	v_add_f32_dpp v0, v18, v18 quad_perm:[1,0,3,2] row_mask:0xf bank_mask:0xf bound_ctrl:1
	v_pk_fma_f32 v[60:61], v[82:83], v[24:25], v[20:21] op_sel_hi:[0,1,1]
	ds_read_b128 v[18:21], v90 offset:2304
	v_add_f32_dpp v0, v0, v0 quad_perm:[2,3,0,1] row_mask:0xf bank_mask:0xf bound_ctrl:1
	ds_read_b128 v[22:25], v89 offset:6400
	ds_read_b128 v[34:37], v90 offset:6400
	v_add_f32_dpp v0, v0, v0 row_half_mirror row_mask:0xf bank_mask:0xf bound_ctrl:1
	ds_read_b128 v[50:53], v90 offset:10496
	ds_read_b128 v[54:57], v89 offset:18688
	v_add_f32_dpp v0, v0, v0 row_ror:8 row_mask:0xf bank_mask:0xf bound_ctrl:1
	s_waitcnt lgkmcnt(7)
	v_pk_fma_f32 v[38:39], v[38:39], v[0:1], v[58:59] op_sel_hi:[1,0,1] neg_lo:[1,0,0] neg_hi:[1,0,0]
	v_pk_fma_f32 v[40:41], v[40:41], v[0:1], v[60:61] op_sel_hi:[1,0,1] neg_lo:[1,0,0] neg_hi:[1,0,0]
	v_pk_mul_f32 v[26:27], v[26:27], v[38:39]
	v_pk_mul_f32 v[44:45], v[44:45], v[40:41]
	v_pk_mul_f32 v[10:11], v[10:11], v[38:39]
	v_pk_fma_f32 v[38:39], v[42:43], v[38:39], v[44:45]
	v_pk_fma_f32 v[26:27], v[28:29], v[40:41], v[26:27]
	v_pk_fma_f32 v[58:59], v[6:7], v[14:15], v[10:11] op_sel_hi:[0,1,1]
	v_add_f32_e32 v99, v38, v39
	v_add_f32_e32 v10, v26, v27
	ds_write_b128 v91, v[96:99] offset:47104
	v_pk_mul_f32 v[12:13], v[12:13], v[40:41]
	v_add_f32_dpp v0, v10, v10 quad_perm:[1,0,3,2] row_mask:0xf bank_mask:0xf bound_ctrl:1
	v_pk_fma_f32 v[60:61], v[6:7], v[16:17], v[12:13] op_sel_hi:[0,1,1]
	ds_read_b128 v[10:13], v90 offset:2560
	v_add_f32_dpp v0, v0, v0 quad_perm:[2,3,0,1] row_mask:0xf bank_mask:0xf bound_ctrl:1
	ds_read_b128 v[14:17], v89 offset:6656
	ds_read_b128 v[26:29], v90 offset:6656
	v_add_f32_dpp v0, v0, v0 row_half_mirror row_mask:0xf bank_mask:0xf bound_ctrl:1
	ds_read_b128 v[38:41], v90 offset:10752
	ds_read_b128 v[42:45], v89 offset:18944
	v_add_f32_dpp v0, v0, v0 row_ror:8 row_mask:0xf bank_mask:0xf bound_ctrl:1
	s_waitcnt lgkmcnt(8)
	v_pk_fma_f32 v[30:31], v[30:31], v[0:1], v[58:59] op_sel_hi:[1,0,1] neg_lo:[1,0,0] neg_hi:[1,0,0]
	v_pk_fma_f32 v[32:33], v[32:33], v[0:1], v[60:61] op_sel_hi:[1,0,1] neg_lo:[1,0,0] neg_hi:[1,0,0]
	v_pk_mul_f32 v[34:35], v[34:35], v[30:31]
	v_pk_mul_f32 v[48:49], v[48:49], v[32:33]
	v_pk_mul_f32 v[18:19], v[18:19], v[30:31]
	v_pk_mul_f32 v[20:21], v[20:21], v[32:33]
	v_pk_fma_f32 v[30:31], v[46:47], v[30:31], v[48:49]
	v_pk_fma_f32 v[32:33], v[36:37], v[32:33], v[34:35]
	v_pk_fma_f32 v[58:59], v[6:7], v[22:23], v[18:19] op_sel:[1,0,0]
	v_add_f32_e32 v18, v32, v33
	v_add_f32_e32 v92, v30, v31
	v_pk_fma_f32 v[6:7], v[6:7], v[24:25], v[20:21] op_sel:[1,0,0]
	v_add_f32_dpp v0, v18, v18 quad_perm:[1,0,3,2] row_mask:0xf bank_mask:0xf bound_ctrl:1
	ds_read_b128 v[18:21], v90 offset:2816
	ds_read_b128 v[22:25], v89 offset:6912
	v_add_f32_dpp v0, v0, v0 quad_perm:[2,3,0,1] row_mask:0xf bank_mask:0xf bound_ctrl:1
	ds_read_b128 v[30:33], v90 offset:6912
	ds_read_b128 v[34:37], v90 offset:11008
	v_add_f32_dpp v0, v0, v0 row_half_mirror row_mask:0xf bank_mask:0xf bound_ctrl:1
	ds_read_b128 v[46:49], v89 offset:19200
	s_nop 0
	v_add_f32_dpp v0, v0, v0 row_ror:8 row_mask:0xf bank_mask:0xf bound_ctrl:1
	s_waitcnt lgkmcnt(7)
	v_pk_fma_f32 v[50:51], v[50:51], v[0:1], v[58:59] op_sel_hi:[1,0,1] neg_lo:[1,0,0] neg_hi:[1,0,0]
	v_pk_fma_f32 v[6:7], v[52:53], v[0:1], v[6:7] op_sel_hi:[1,0,1] neg_lo:[1,0,0] neg_hi:[1,0,0]
	v_pk_mul_f32 v[26:27], v[26:27], v[50:51]
	v_pk_mul_f32 v[52:53], v[56:57], v[6:7]
	v_pk_mul_f32 v[10:11], v[10:11], v[50:51]
	v_pk_mul_f32 v[12:13], v[12:13], v[6:7]
	v_pk_fma_f32 v[50:51], v[54:55], v[50:51], v[52:53]
	v_pk_fma_f32 v[6:7], v[28:29], v[6:7], v[26:27]
	v_add_f32_e32 v6, v6, v7
	v_add_f32_e32 v93, v50, v51
	v_pk_fma_f32 v[54:55], v[8:9], v[14:15], v[10:11] op_sel_hi:[0,1,1]
	v_add_f32_dpp v0, v6, v6 quad_perm:[1,0,3,2] row_mask:0xf bank_mask:0xf bound_ctrl:1
	v_pk_fma_f32 v[56:57], v[8:9], v[16:17], v[12:13] op_sel_hi:[0,1,1]
	ds_read_b128 v[6:9], v90 offset:3072
	v_add_f32_dpp v0, v0, v0 quad_perm:[2,3,0,1] row_mask:0xf bank_mask:0xf bound_ctrl:1
	ds_read_b128 v[10:13], v89 offset:7168
	ds_read_b128 v[14:17], v90 offset:7168
	v_add_f32_dpp v0, v0, v0 row_half_mirror row_mask:0xf bank_mask:0xf bound_ctrl:1
	ds_read_b128 v[26:29], v90 offset:11264
	ds_read_b128 v[50:53], v89 offset:19456
	v_add_f32_dpp v0, v0, v0 row_ror:8 row_mask:0xf bank_mask:0xf bound_ctrl:1
	s_waitcnt lgkmcnt(7)
	v_pk_fma_f32 v[38:39], v[38:39], v[0:1], v[54:55] op_sel_hi:[1,0,1] neg_lo:[1,0,0] neg_hi:[1,0,0]
	v_pk_fma_f32 v[40:41], v[40:41], v[0:1], v[56:57] op_sel_hi:[1,0,1] neg_lo:[1,0,0] neg_hi:[1,0,0]
	v_pk_mul_f32 v[30:31], v[30:31], v[38:39]
	v_pk_mul_f32 v[44:45], v[44:45], v[40:41]
	v_pk_mul_f32 v[18:19], v[18:19], v[38:39]
	v_pk_fma_f32 v[38:39], v[42:43], v[38:39], v[44:45]
	v_pk_fma_f32 v[30:31], v[32:33], v[40:41], v[30:31]
	v_pk_fma_f32 v[54:55], v[84:85], v[22:23], v[18:19] op_sel_hi:[0,1,1]
	v_add_f32_e32 v18, v30, v31
	v_add_f32_e32 v94, v38, v39
	v_pk_mul_f32 v[20:21], v[20:21], v[40:41]
	v_add_f32_dpp v0, v18, v18 quad_perm:[1,0,3,2] row_mask:0xf bank_mask:0xf bound_ctrl:1
	v_pk_fma_f32 v[56:57], v[84:85], v[24:25], v[20:21] op_sel_hi:[0,1,1]
	ds_read_b128 v[18:21], v90 offset:3328
	v_add_f32_dpp v0, v0, v0 quad_perm:[2,3,0,1] row_mask:0xf bank_mask:0xf bound_ctrl:1
	ds_read_b128 v[22:25], v89 offset:7424
	ds_read_b128 v[30:33], v90 offset:7424
	v_add_f32_dpp v0, v0, v0 row_half_mirror row_mask:0xf bank_mask:0xf bound_ctrl:1
	ds_read_b128 v[38:41], v90 offset:11520
	ds_read_b128 v[42:45], v89 offset:19712
	v_add_f32_dpp v0, v0, v0 row_ror:8 row_mask:0xf bank_mask:0xf bound_ctrl:1
	s_waitcnt lgkmcnt(7)
	v_pk_fma_f32 v[34:35], v[34:35], v[0:1], v[54:55] op_sel_hi:[1,0,1] neg_lo:[1,0,0] neg_hi:[1,0,0]
	v_pk_fma_f32 v[36:37], v[36:37], v[0:1], v[56:57] op_sel_hi:[1,0,1] neg_lo:[1,0,0] neg_hi:[1,0,0]
	v_pk_mul_f32 v[14:15], v[14:15], v[34:35]
	v_pk_mul_f32 v[48:49], v[48:49], v[36:37]
	v_pk_mul_f32 v[6:7], v[6:7], v[34:35]
	v_pk_fma_f32 v[34:35], v[46:47], v[34:35], v[48:49]
	v_pk_fma_f32 v[14:15], v[16:17], v[36:37], v[14:15]
	v_pk_fma_f32 v[54:55], v[2:3], v[10:11], v[6:7] op_sel_hi:[0,1,1]
	v_add_f32_e32 v95, v34, v35
	v_add_f32_e32 v6, v14, v15
	ds_write_b128 v91, v[92:95] offset:51200
	v_pk_mul_f32 v[8:9], v[8:9], v[36:37]
	v_add_f32_dpp v0, v6, v6 quad_perm:[1,0,3,2] row_mask:0xf bank_mask:0xf bound_ctrl:1
	v_pk_fma_f32 v[56:57], v[2:3], v[12:13], v[8:9] op_sel_hi:[0,1,1]
	ds_read_b128 v[6:9], v90 offset:3584
	v_add_f32_dpp v0, v0, v0 quad_perm:[2,3,0,1] row_mask:0xf bank_mask:0xf bound_ctrl:1
	ds_read_b128 v[10:13], v89 offset:7680
	ds_read_b128 v[14:17], v90 offset:7680
	v_add_f32_dpp v0, v0, v0 row_half_mirror row_mask:0xf bank_mask:0xf bound_ctrl:1
	ds_read_b128 v[34:37], v90 offset:11776
	ds_read_b128 v[46:49], v89 offset:19968
	v_add_f32_dpp v0, v0, v0 row_ror:8 row_mask:0xf bank_mask:0xf bound_ctrl:1
	s_waitcnt lgkmcnt(8)
	v_pk_fma_f32 v[26:27], v[26:27], v[0:1], v[54:55] op_sel_hi:[1,0,1] neg_lo:[1,0,0] neg_hi:[1,0,0]
	v_pk_fma_f32 v[28:29], v[28:29], v[0:1], v[56:57] op_sel_hi:[1,0,1] neg_lo:[1,0,0] neg_hi:[1,0,0]
	v_pk_mul_f32 v[30:31], v[30:31], v[26:27]
	v_pk_mul_f32 v[52:53], v[52:53], v[28:29]
	v_pk_mul_f32 v[18:19], v[18:19], v[26:27]
	v_pk_mul_f32 v[20:21], v[20:21], v[28:29]
	v_pk_fma_f32 v[26:27], v[50:51], v[26:27], v[52:53]
	v_pk_fma_f32 v[28:29], v[32:33], v[28:29], v[30:31]
	v_pk_fma_f32 v[54:55], v[2:3], v[22:23], v[18:19] op_sel:[1,0,0]
	v_add_f32_e32 v18, v28, v29
	v_add_f32_e32 v96, v26, v27
	v_pk_fma_f32 v[2:3], v[2:3], v[24:25], v[20:21] op_sel:[1,0,0]
	v_add_f32_dpp v0, v18, v18 quad_perm:[1,0,3,2] row_mask:0xf bank_mask:0xf bound_ctrl:1
	ds_read_b128 v[18:21], v90 offset:3840
	ds_read_b128 v[22:25], v89 offset:7936
	v_add_f32_dpp v0, v0, v0 quad_perm:[2,3,0,1] row_mask:0xf bank_mask:0xf bound_ctrl:1
	ds_read_b128 v[26:29], v90 offset:7936
	ds_read_b128 v[30:33], v90 offset:12032
	v_add_f32_dpp v0, v0, v0 row_half_mirror row_mask:0xf bank_mask:0xf bound_ctrl:1
	ds_read_b128 v[50:53], v89 offset:20224
	s_nop 0
	v_add_f32_dpp v0, v0, v0 row_ror:8 row_mask:0xf bank_mask:0xf bound_ctrl:1
	s_waitcnt lgkmcnt(7)
	v_pk_fma_f32 v[38:39], v[38:39], v[0:1], v[54:55] op_sel_hi:[1,0,1] neg_lo:[1,0,0] neg_hi:[1,0,0]
	v_pk_fma_f32 v[2:3], v[40:41], v[0:1], v[2:3] op_sel_hi:[1,0,1] neg_lo:[1,0,0] neg_hi:[1,0,0]
	v_pk_mul_f32 v[14:15], v[14:15], v[38:39]
	v_pk_mul_f32 v[40:41], v[44:45], v[2:3]
	v_pk_mul_f32 v[8:9], v[8:9], v[2:3]
	v_pk_fma_f32 v[2:3], v[16:17], v[2:3], v[14:15]
	v_pk_mul_f32 v[6:7], v[6:7], v[38:39]
	v_add_f32_e32 v0, v2, v3
	v_pk_fma_f32 v[6:7], v[4:5], v[10:11], v[6:7] op_sel_hi:[0,1,1]
	v_pk_fma_f32 v[4:5], v[4:5], v[12:13], v[8:9] op_sel_hi:[0,1,1]
	v_add_f32_dpp v0, v0, v0 quad_perm:[1,0,3,2] row_mask:0xf bank_mask:0xf bound_ctrl:1
	v_pk_fma_f32 v[38:39], v[42:43], v[38:39], v[40:41]
	ds_read_b128 v[108:111], v88 offset:4096
	v_add_f32_dpp v0, v0, v0 quad_perm:[2,3,0,1] row_mask:0xf bank_mask:0xf bound_ctrl:1
	v_add_f32_e32 v97, v38, v39
	ds_read_b128 v[100:103], v88
	v_add_f32_dpp v0, v0, v0 row_half_mirror row_mask:0xf bank_mask:0xf bound_ctrl:1
	ds_read_b128 v[120:123], v88 offset:8192
	ds_read_b128 v[112:115], v88 offset:4352
	v_add_f32_dpp v0, v0, v0 row_ror:8 row_mask:0xf bank_mask:0xf bound_ctrl:1
	s_waitcnt lgkmcnt(6)
	v_pk_fma_f32 v[2:3], v[34:35], v[0:1], v[6:7] op_sel_hi:[1,0,1] neg_lo:[1,0,0] neg_hi:[1,0,0]
	v_pk_fma_f32 v[4:5], v[36:37], v[0:1], v[4:5] op_sel_hi:[1,0,1] neg_lo:[1,0,0] neg_hi:[1,0,0]
	v_pk_mul_f32 v[8:9], v[26:27], v[2:3]
	v_pk_mul_f32 v[6:7], v[48:49], v[4:5]
	v_pk_mul_f32 v[10:11], v[18:19], v[2:3]
	v_pk_mul_f32 v[12:13], v[20:21], v[4:5]
	v_pk_fma_f32 v[2:3], v[46:47], v[2:3], v[6:7]
	v_pk_fma_f32 v[4:5], v[28:29], v[4:5], v[8:9]
	v_add_f32_e32 v98, v2, v3
	v_add_f32_e32 v2, v4, v5
	v_pk_fma_f32 v[8:9], v[86:87], v[24:25], v[12:13] op_sel_hi:[0,1,1]
	s_nop 0
	v_add_f32_dpp v0, v2, v2 quad_perm:[1,0,3,2] row_mask:0xf bank_mask:0xf bound_ctrl:1
	v_pk_fma_f32 v[6:7], v[86:87], v[22:23], v[10:11] op_sel_hi:[0,1,1]
	ds_read_b128 v[104:107], v88 offset:256
	v_add_f32_dpp v0, v0, v0 quad_perm:[2,3,0,1] row_mask:0xf bank_mask:0xf bound_ctrl:1
	ds_read_b128 v[128:131], v88 offset:8448
	ds_read_b128 v[124:127], v88 offset:4608
	v_add_f32_dpp v0, v0, v0 row_half_mirror row_mask:0xf bank_mask:0xf bound_ctrl:1
	ds_read_b128 v[116:119], v88 offset:512
	s_nop 0
	v_add_f32_dpp v0, v0, v0 row_ror:8 row_mask:0xf bank_mask:0xf bound_ctrl:1
	s_waitcnt lgkmcnt(8)
	v_pk_fma_f32 v[76:77], v[32:33], v[0:1], v[8:9] op_sel_hi:[1,0,1] neg_lo:[1,0,0] neg_hi:[1,0,0]
	v_pk_fma_f32 v[74:75], v[30:31], v[0:1], v[6:7] op_sel_hi:[1,0,1] neg_lo:[1,0,0] neg_hi:[1,0,0]
	v_pk_mul_f32 v[2:3], v[52:53], v[76:77]
	s_nop 0
	v_pk_fma_f32 v[2:3], v[50:51], v[74:75], v[2:3]
	s_nop 0
	v_add_f32_e32 v99, v2, v3
	ds_write_b128 v91, v[96:99] offset:55296
	s_and_b32 s2, s26, 1
	s_mul_i32 s3, s2, 0x5400
	v_lshlrev_b32_e32 v91, 2, v87
	v_lshl_add_u32 v91, s2, 14, v91
	s_add_i32 s2, s3, 0
	v_add_u32_e32 v0, s2, v85
	v_add_u32_e32 v89, s2, v83
	v_add_u32_e32 v90, s96, v83
	s_add_i32 s96, s96, 0x3000
	s_cmp_eq_u32 s96, 0x1e800
	s_cselect_b32 s96, 0x20200, s96
	s_cmp_eq_u32 s96, 0x23200
	s_cselect_b32 s96, 0x12800, s96
	v_add_u32_e32 v88, s96, v83
	s_cmpk_eq_i32 s26, 0x110
	s_waitcnt lgkmcnt(0)
	s_barrier
	s_cbranch_scc0 .LBB0_1050
	s_setprio 0
